# phase 2: prompt scans assigned statically, 16 per XCD (even spread)
# speedup vs baseline: 1.0098x; 1.0098x over previous
; #define LAUNDER_TID(t) int t = (g_wave << 6) | (int)__builtin_amdgcn_mbcnt_hi(~0u, __builtin_amdgcn_mbcnt_lo(~0u, 0u)); asm volatile("" : "+v"(t))
; DI void phase2(const Params& p, char* smem, const int g_wave) {
;     ...
;   for (;;) {
;     { LAUNDER_TID(tq); if (tq == 0) s_item = atomicAdd(ctr, 1); }
;     __syncthreads();
;     const int it = __builtin_amdgcn_readfirstlane(s_item);
;     __syncthreads();
;     if (it >= N3) break;
;     const bool is_scan = it < N0 || (it >= N1 && it < N2);
.LBB0_679:
	s_or_b64 exec, exec, s[0:1]
	s_and_b32 s0, s75, 0xffffffc0
	s_cmpk_lt_u32 s75, 0x80
	s_cselect_b32 s2, 17, 0
	s_lshr_b32 s28, s75, 7
	s_add_i32 s28, s28, 1
	s_cmpk_gt_u32 s75, 0xff
	s_cselect_b64 s[8:9], -1, 0
	s_lshl_b32 s29, s3, 3
	v_or_b32_e32 v196, s0, v2
	s_movk_i32 s6, 0x80
	v_cmp_gt_u32_e64 s[10:11], s6, v196
	s_and_saveexec_b64 s[4:5], s[10:11]
	v_lshlrev_b32_e32 v6, 2, v196
	global_load_dword v7, v6, s[44:45]
	v_add_u32_e32 v6, 0x25100, v6
	s_waitcnt vmcnt(0)
	ds_write_b32 v6, v7
	s_or_b64 exec, exec, s[4:5]
	s_sub_i32 s30, s29, 32
	s_lshl_b32 s0, s3, 4
	s_add_u32 s33, s72, 0x9641000
	s_addc_u32 s75, s73, 0
	v_writelane_b32 v255, s0, 9
	s_add_u32 s0, s72, 0x19741000
	v_writelane_b32 v255, s0, 17
	s_addc_u32 s0, s73, 0
	v_writelane_b32 v255, s0, 19
	s_add_u32 s0, s72, 0x11741000
	v_writelane_b32 v255, s0, 21
	s_addc_u32 s0, s73, 0
	v_writelane_b32 v255, s0, 23
	s_add_u32 s0, s72, 0x22841000
	v_writelane_b32 v255, s0, 10
	s_addc_u32 s0, s73, 0
	v_writelane_b32 v255, s0, 15
	s_add_u32 s0, s72, 0x1a841000
	v_writelane_b32 v255, s0, 11
	s_addc_u32 s0, s73, 0
	s_add_u32 s10, s72, 0x23941000
	s_addc_u32 s11, s73, 0
	v_writelane_b32 v255, s0, 13
	s_add_u32 s0, s70, 0x8100000
	s_addc_u32 s95, s71, 0
	s_add_u32 s16, s72, 0x239a3700
	s_addc_u32 s17, s73, 0
	s_add_u32 s18, s72, 0x239a5000
	v_writelane_b32 v255, s0, 12
	s_addc_u32 s19, s73, 0
	s_lshl_b32 s0, s3, 6
	s_add_i32 s96, s0, 16
	s_add_i32 s96, s96, 0xa100
	v_mov_b32_e32 v3, 0
	s_mov_b64 s[24:25], 0x80
	s_mov_b64 s[26:27], 0x20000
	s_mov_b32 s97, 0x3e38aa3b
	s_mov_b32 s3, 1.0
	s_mov_b32 s98, 0x800000
	s_add_i32 s99, 16, 0x1e700
	s_add_i32 s36, 16, 0x1f800
	s_movk_i32 s37, 0x90
	s_add_i32 s31, 16, 0x1ec00
	s_movk_i32 s86, 0x1900
	s_movk_i32 s87, 0x1000
	s_add_i32 s88, 16, 0x1c300
	s_movk_i32 s89, 0x7fff
	s_mov_b32 s90, 0x7060302
	s_add_i32 s91, 16, 0x1d500
	v_mov_b32_e32 v197, 0x3a27c5ac
	s_add_i32 s92, 16, 0x1a180
	s_add_i32 s93, 16, 0x18180
	s_add_i32 s94, 16, 0x100
	v_mov_b32_e32 v183, 1.0
	v_readlane_b32 s6, v255, 0
	s_nop 3
	s_lshr_b32 s4, s6, 3
	s_cmp_lt_u32 s4, 16
	s_cbranch_scc0 .LBB0_683
	s_and_b32 s6, s6, 7
	s_lshl_b32 s6, s6, 4
	s_add_i32 s6, s6, s4
	v_mov_b32_e32 v2, v196
	s_mov_b64 s[0:1], -1
	s_branch .Lq_static
